# grid barrier: non-leader workgroups sleep 14 between polls of the generation word
# baseline (speedup 1.0000x reference)
; DI unsigned xb_ld(unsigned* p)              { return __hip_atomic_load(p, __ATOMIC_RELAXED, __HIP_MEMORY_SCOPE_AGENT); }
; DI unsigned xb_add(unsigned* p, unsigned v) { return __hip_atomic_fetch_add(p, v, __ATOMIC_RELAXED, __HIP_MEMORY_SCOPE_AGENT); }
; #define XB_SPIN(cond, bar) do { unsigned _sp = 0; while (cond) { __builtin_amdgcn_s_sleep(1); \
;     if ((++_sp & 255u) == 0u) { if (xb_ld(&(bar)[XB_TMO])) break; if (_sp > XB_SPIN_CAP) { atomicAdd(&(bar)[XB_TMO], 1u); break; } } } } while (0)
; DI void xcd_barrier(const XcdBarrier& b) {
;     ...
;             else XB_SPIN(xb_ld(&bar[XB_TOPGEN]) == tg, bar);
;             __builtin_amdgcn_fence(__ATOMIC_ACQUIRE, "agent");
;             xb_add(&bar[XB_XGEN(b.x)], 1u);
;             asm volatile("s_waitcnt vmcnt(0)" ::: "memory");
;         } else {
;             XB_SPIN(xb_ld(&bar[XB_XGEN(b.x)]) == gen, bar);
;             __builtin_amdgcn_fence(__ATOMIC_ACQUIRE, "agent");
;             asm volatile("s_waitcnt vmcnt(0)" ::: "memory");
;         }
.LBB0_375:
	s_and_b32 s42, s46, 0xff
	s_mov_b64 s[40:41], -1
	s_cmp_lg_u32 s42, 0
	s_mov_b64 s[44:45], -1
	s_sleep 14
	s_cbranch_scc0 .LBB0_378
	s_and_b64 vcc, exec, s[44:45]
	s_cbranch_vccz .LBB0_374
